# combined: P1 row rewrite + early K LDS writes + counted PV waits + scalar fma + chunk-gate fixes on the attention-rescheduled build
# baseline (speedup 1.0000x reference)
.LBB0_433:
	ds_read_b128 v[64:67], v166 offset:49152
	ds_read_b128 v[68:71], v166 offset:57344
	ds_read_b128 v[176:179], v167 offset:49152
	ds_read_b128 v[198:201], v167 offset:57344
	ds_read_b128 v[202:205], v168 offset:49152
	ds_read_b128 v[210:213], v168 offset:57344
	v_exp_f32_e32 v142, v142
	v_exp_f32_e32 v143, v143
	s_waitcnt lgkmcnt(5)
	v_mfma_f32_32x32x16_bf16 v[80:95], v[64:67], v[124:127], 0
	v_exp_f32_e32 v180, v140
	v_exp_f32_e32 v181, v141
	v_exp_f32_e32 v206, v138
	v_exp_f32_e32 v207, v135
	v_exp_f32_e32 v148, v148
	v_exp_f32_e32 v149, v149
	v_exp_f32_e32 v209, v146
	s_waitcnt lgkmcnt(4)
	v_mfma_f32_32x32x16_bf16 v[64:79], v[68:71], v[124:127], 0
	v_cvt_pk_bf16_f32 v135, v192, v193
	v_cvt_pk_bf16_f32 v138, v182, v183
	v_cvt_pk_bf16_f32 v140, v185, v187
	v_cvt_pk_bf16_f32 v141, v188, v189
	s_nop 0
	s_waitcnt lgkmcnt(3)
	v_mfma_f32_32x32x16_bf16 v[80:95], v[176:179], v[120:123], v[80:95]
	ds_read_b128 v[176:179], v169 offset:49152
	ds_read_b128 v[214:217], v169 offset:57344
	ds_read_b128 v[218:221], v170 offset:49152
	ds_read_b128 v[222:225], v170 offset:57344
	ds_read_b128 v[226:229], v171 offset:49152
	ds_read_b128 v[230:233], v171 offset:57344
	ds_read_b128 v[234:237], v172 offset:49152
	ds_read_b128 v[238:241], v172 offset:57344
	s_waitcnt lgkmcnt(10)
	v_mfma_f32_32x32x16_bf16 v[64:79], v[198:201], v[120:123], v[64:79]
	ds_read_b128 v[198:201], v173 offset:49152
	ds_read_b128 v[242:245], v173 offset:57344
	s_waitcnt lgkmcnt(11)
	v_mfma_f32_32x32x16_bf16 v[80:95], v[202:205], v[112:115], v[80:95]
	v_exp_f32_e32 v205, v134
	v_add_f32_e32 v134, v191, v190
	v_add_f32_e32 v134, v192, v134
	v_add_f32_e32 v134, v193, v134
	v_add_f32_e32 v134, v194, v134
	v_add_f32_e32 v134, v196, v134
	s_waitcnt lgkmcnt(10)
	v_mfma_f32_32x32x16_bf16 v[64:79], v[210:213], v[112:115], v[64:79]
	v_add_f32_e32 v134, v195, v134
	v_add_f32_e32 v134, v197, v134
	v_add_f32_e32 v134, v182, v134
	v_add_f32_e32 v134, v183, v134
	v_add_f32_e32 v134, v184, v134
	v_add_f32_e32 v134, v186, v134
	v_add_f32_e32 v134, v185, v134
	s_waitcnt lgkmcnt(9)
	v_mfma_f32_32x32x16_bf16 v[80:95], v[176:179], v[116:119], v[80:95]
	v_add_f32_e32 v134, v187, v134
	v_add_f32_e32 v134, v188, v134
	v_add_f32_e32 v134, v189, v134
	v_add_f32_e32 v134, v142, v134
	v_exp_f32_e32 v202, v139
	v_add_f32_e32 v134, v143, v134
	v_exp_f32_e32 v203, v136
	s_waitcnt lgkmcnt(8)
	v_mfma_f32_32x32x16_bf16 v[64:79], v[214:217], v[116:119], v[64:79]
	v_add_f32_e32 v134, v180, v134
	v_exp_f32_e32 v204, v137
	v_add_f32_e32 v134, v181, v134
	v_add_f32_e32 v134, v206, v134
	v_add_f32_e32 v134, v202, v134
	v_add_f32_e32 v134, v203, v134
	v_add_f32_e32 v134, v204, v134
	s_waitcnt lgkmcnt(7)
	v_mfma_f32_32x32x16_bf16 v[80:95], v[218:221], v[108:111], v[80:95]
	v_add_f32_e32 v134, v205, v134
	v_exp_f32_e32 v210, v147
	v_add_f32_e32 v134, v207, v134
	v_exp_f32_e32 v211, v144
	v_add_f32_e32 v134, v148, v134
	v_exp_f32_e32 v212, v145
	v_add_f32_e32 v134, v149, v134
	s_waitcnt lgkmcnt(6)
	v_mfma_f32_32x32x16_bf16 v[64:79], v[222:225], v[108:111], v[64:79]
	v_add_f32_e32 v134, v209, v134
	v_add_f32_e32 v134, v210, v134
	v_add_f32_e32 v134, v211, v134
	v_add_f32_e32 v176, v212, v134
	v_cvt_pk_bf16_f32 v134, v190, v191
	v_cvt_pk_bf16_f32 v136, v194, v196
	s_waitcnt lgkmcnt(5)
	v_mfma_f32_32x32x16_bf16 v[80:95], v[226:229], v[104:107], v[80:95]
	v_cvt_pk_bf16_f32 v137, v195, v197
	v_cvt_pk_bf16_f32 v139, v184, v186
	v_cvt_pk_bf16_f32 v142, v142, v143
	s_waitcnt lgkmcnt(4)
	v_mfma_f32_32x32x16_bf16 v[64:79], v[230:233], v[104:107], v[64:79]
	v_cvt_pk_bf16_f32 v143, v180, v181
	v_cvt_pk_bf16_f32 v144, v206, v202
	v_cvt_pk_bf16_f32 v145, v203, v204
	v_cvt_pk_bf16_f32 v146, v205, v207
	v_cvt_pk_bf16_f32 v147, v148, v149
	v_cvt_pk_bf16_f32 v148, v209, v210
	v_cvt_pk_bf16_f32 v149, v211, v212
	s_waitcnt lgkmcnt(3)
	v_mfma_f32_32x32x16_bf16 v[80:95], v[234:237], v[100:103], v[80:95]
	s_waitcnt lgkmcnt(2)
	v_mfma_f32_32x32x16_bf16 v[64:79], v[238:241], v[100:103], v[64:79]
	s_waitcnt lgkmcnt(1)
	v_mfma_f32_32x32x16_bf16 v[80:95], v[198:201], v[96:99], v[80:95]
	s_waitcnt lgkmcnt(0)
	v_mfma_f32_32x32x16_bf16 v[64:79], v[242:245], v[96:99], v[64:79]
	global_load_dwordx4 v[218:221], v132, s[28:29]
	global_load_dwordx4 v[222:225], v133, s[28:29]
	global_load_dwordx4 v[226:229], v132, s[30:31]
	global_load_dwordx4 v[230:233], v133, s[30:31]
	s_add_u32 s28, s28, 0x8000
	s_addc_u32 s29, s29, 0
	s_add_u32 s30, s30, 0x8000
	s_addc_u32 s31, s31, 0
	ds_read_b64_tr_b16 v[196:197], v161 offset:0
	ds_read_b64_tr_b16 v[198:199], v161 offset:0x800
	ds_read_b64_tr_b16 v[200:201], v161 offset:0x1000
	ds_read_b64_tr_b16 v[202:203], v161 offset:0x1800
	ds_read_b64_tr_b16 v[204:205], v161 offset:0x2000
	ds_read_b64_tr_b16 v[206:207], v161 offset:0x2800
	ds_read_b64_tr_b16 v[210:211], v161 offset:0x3000
	ds_read_b64_tr_b16 v[212:213], v161 offset:0x3800
	s_nop 0
	s_waitcnt lgkmcnt(6)
	v_mfma_f32_32x32x16_bf16 v[0:15], v[134:137], v[196:199], v[0:15]
	ds_read_b64_tr_b16 v[196:197], v161 offset:0x200
	ds_read_b64_tr_b16 v[198:199], v161 offset:0xa00
	v_max_f32_e32 v234, v80, v81
	v_max3_f32 v234, v234, v82, v83
	v_max3_f32 v234, v234, v84, v85
	v_max3_f32 v234, v234, v86, v87
	v_max3_f32 v234, v234, v88, v89
	s_waitcnt lgkmcnt(6)
	v_mfma_f32_32x32x16_bf16 v[0:15], v[138:141], v[200:203], v[0:15]
	ds_read_b64_tr_b16 v[200:201], v161 offset:0x1200
	ds_read_b64_tr_b16 v[202:203], v161 offset:0x1a00
	v_max3_f32 v234, v234, v90, v91
	v_max3_f32 v234, v234, v92, v93
	v_max3_f32 v234, v234, v94, v95
	v_max3_f32 v234, v234, v64, v65
	v_max3_f32 v234, v234, v66, v67
	s_waitcnt lgkmcnt(6)
	v_mfma_f32_32x32x16_bf16 v[0:15], v[142:145], v[204:207], v[0:15]
	ds_read_b64_tr_b16 v[204:205], v161 offset:0x2200
	ds_read_b64_tr_b16 v[206:207], v161 offset:0x2a00
	ds_read_b64_tr_b16 v[214:215], v161 offset:0x3200
	ds_read_b64_tr_b16 v[216:217], v161 offset:0x3a00
	v_max3_f32 v234, v234, v68, v69
	v_max3_f32 v234, v234, v70, v71
	v_max3_f32 v234, v234, v72, v73
	v_max3_f32 v234, v234, v74, v75
	v_max3_f32 v234, v234, v76, v77
	s_waitcnt lgkmcnt(8)
	v_mfma_f32_32x32x16_bf16 v[0:15], v[146:149], v[210:213], v[0:15]
	v_max3_f32 v234, v234, v78, v79
	v_mov_b32_e32 v235, v234
	s_waitcnt lgkmcnt(6)
	v_mfma_f32_32x32x16_bf16 v[48:63], v[134:137], v[196:199], v[48:63]
	ds_read_b64_tr_b16 v[196:197], v161 offset:0x400
	ds_read_b64_tr_b16 v[198:199], v161 offset:0xc00
	v_permlane32_swap_b32_e32 v234, v235
	v_max_f32_e32 v234, v234, v235
	s_waitcnt lgkmcnt(6)
	v_mfma_f32_32x32x16_bf16 v[48:63], v[138:141], v[200:203], v[48:63]
	ds_read_b64_tr_b16 v[200:201], v161 offset:0x1400
	ds_read_b64_tr_b16 v[202:203], v161 offset:0x1c00
	v_sub_f32_e32 v235, v234, v175
	v_max_f32_e32 v234, v175, v234
	v_sub_f32_e32 v236, v175, v234
	v_mul_f32_e32 v236, 0x3e0293ee, v236
	s_waitcnt lgkmcnt(6)
	v_mfma_f32_32x32x16_bf16 v[48:63], v[142:145], v[204:207], v[48:63]
	ds_read_b64_tr_b16 v[204:205], v161 offset:0x2400
	ds_read_b64_tr_b16 v[206:207], v161 offset:0x2c00
	ds_read_b64_tr_b16 v[210:211], v161 offset:0x3400
	ds_read_b64_tr_b16 v[212:213], v161 offset:0x3c00
	v_exp_f32_e32 v236, v236
	v_cmp_ge_f32_e32 vcc, s15, v235
	s_cmp_eq_u64 vcc, exec
	s_cselect_b64 s[8:9], -1, 0
	s_waitcnt lgkmcnt(8)
	v_mfma_f32_32x32x16_bf16 v[48:63], v[146:149], v[214:217], v[48:63]
	v_cndmask_b32_e64 v179, v236, 1.0, s[8:9]
	v_cndmask_b32_e64 v234, v234, v175, s[8:9]
	v_mul_f32_e32 v238, 0xbe0293ee, v234
	v_fmamk_f32 v88, v88, 0x3e0293ee, v238
	v_fmamk_f32 v89, v89, 0x3e0293ee, v238
	v_fmamk_f32 v80, v80, 0x3e0293ee, v238
	v_fmamk_f32 v81, v81, 0x3e0293ee, v238
	s_waitcnt lgkmcnt(6)
	v_mfma_f32_32x32x16_bf16 v[32:47], v[134:137], v[196:199], v[32:47]
	ds_read_b64_tr_b16 v[196:197], v161 offset:0x600
	ds_read_b64_tr_b16 v[198:199], v161 offset:0xe00
	v_fmamk_f32 v82, v82, 0x3e0293ee, v238
	v_fmamk_f32 v83, v83, 0x3e0293ee, v238
	v_fmamk_f32 v84, v84, 0x3e0293ee, v238
	v_fmamk_f32 v85, v85, 0x3e0293ee, v238
	v_fmamk_f32 v86, v86, 0x3e0293ee, v238
	v_fmamk_f32 v87, v87, 0x3e0293ee, v238
	v_fmamk_f32 v90, v90, 0x3e0293ee, v238
	v_fmamk_f32 v91, v91, 0x3e0293ee, v238
	s_waitcnt lgkmcnt(6)
	v_mfma_f32_32x32x16_bf16 v[32:47], v[138:141], v[200:203], v[32:47]
	ds_read_b64_tr_b16 v[200:201], v161 offset:0x1600
	ds_read_b64_tr_b16 v[202:203], v161 offset:0x1e00
	v_fmamk_f32 v92, v92, 0x3e0293ee, v238
	v_fmamk_f32 v93, v93, 0x3e0293ee, v238
	v_fmamk_f32 v94, v94, 0x3e0293ee, v238
	v_fmamk_f32 v95, v95, 0x3e0293ee, v238
	v_fmamk_f32 v188, v64, 0x3e0293ee, v238
	v_fmamk_f32 v189, v65, 0x3e0293ee, v238
	v_fmamk_f32 v190, v66, 0x3e0293ee, v238
	v_fmamk_f32 v191, v67, 0x3e0293ee, v238
	s_waitcnt lgkmcnt(6)
	v_mfma_f32_32x32x16_bf16 v[32:47], v[142:145], v[204:207], v[32:47]
	ds_read_b64_tr_b16 v[204:205], v161 offset:0x2600
	ds_read_b64_tr_b16 v[206:207], v161 offset:0x2e00
	ds_read_b64_tr_b16 v[214:215], v161 offset:0x3600
	ds_read_b64_tr_b16 v[216:217], v161 offset:0x3e00
	v_fmamk_f32 v182, v70, 0x3e0293ee, v238
	v_fmamk_f32 v183, v71, 0x3e0293ee, v238
	v_fmamk_f32 v184, v72, 0x3e0293ee, v238
	v_fmamk_f32 v185, v73, 0x3e0293ee, v238
	v_fmamk_f32 v186, v74, 0x3e0293ee, v238
	v_fmamk_f32 v187, v75, 0x3e0293ee, v238
	s_waitcnt lgkmcnt(8)
	v_mfma_f32_32x32x16_bf16 v[32:47], v[146:149], v[210:213], v[32:47]
	v_fmamk_f32 v192, v68, 0x3e0293ee, v238
	v_fmamk_f32 v181, v69, 0x3e0293ee, v238
	v_fmamk_f32 v180, v76, 0x3e0293ee, v238
	s_waitcnt lgkmcnt(6)
	v_mfma_f32_32x32x16_bf16 v[16:31], v[134:137], v[196:199], v[16:31]
	v_fmamk_f32 v193, v77, 0x3e0293ee, v238
	v_fmamk_f32 v194, v78, 0x3e0293ee, v238
	v_fmamk_f32 v177, v79, 0x3e0293ee, v238
	v_mov_b32_e32 v134, v234
	v_exp_f32_e32 v135, v88
	v_exp_f32_e32 v136, v89
	v_exp_f32_e32 v137, v90
	s_waitcnt lgkmcnt(4)
	v_mfma_f32_32x32x16_bf16 v[16:31], v[138:141], v[200:203], v[16:31]
	v_exp_f32_e32 v139, v91
	v_exp_f32_e32 v138, v92
	v_exp_f32_e32 v140, v93
	v_exp_f32_e32 v141, v94
	s_waitcnt lgkmcnt(2)
	v_mfma_f32_32x32x16_bf16 v[16:31], v[142:145], v[204:207], v[16:31]
	v_exp_f32_e32 v142, v95
	v_exp_f32_e32 v143, v80
	v_exp_f32_e32 v144, v81
	v_exp_f32_e32 v145, v82
	s_waitcnt lgkmcnt(0)
	v_mfma_f32_32x32x16_bf16 v[16:31], v[146:149], v[214:217], v[16:31]
	v_exp_f32_e32 v146, v83
	v_exp_f32_e32 v147, v84
	v_exp_f32_e32 v149, v85
	v_exp_f32_e32 v148, v86
	v_exp_f32_e32 v175, v87
	v_cmp_gt_f32_e32 vcc, 1.0, v179
	s_waitcnt vmcnt(0)
	ds_write_b128 v162, v[226:229] offset:32768
	ds_write_b128 v163, v[230:233] offset:32768
	s_barrier
	s_waitcnt vmcnt(0)
	ds_write_b128 v164, v[218:221]
	ds_write_b128 v165, v[222:225]
	s_cbranch_vccz .LBB0_437
	s_and_saveexec_b64 s[2:3], s[6:7]
	ds_write_b32 v158, v179 offset:128
	s_or_b64 exec, exec, s[2:3]
	s_waitcnt lgkmcnt(0)
	v_add_u32_e32 v234, v131, v128
	ds_read_b128 v[218:221], v234 offset:224
	ds_read_b128 v[222:225], v234 offset:192
	ds_read_b128 v[226:229], v234 offset:160
	ds_read_b128 v[230:233], v234 offset:128
	s_waitcnt lgkmcnt(3)
	v_pk_mul_f32 v[12:13], v[12:13], v[218:219]
	s_waitcnt lgkmcnt(2)
	v_pk_mul_f32 v[8:9], v[8:9], v[222:223]
	s_waitcnt lgkmcnt(1)
	v_pk_mul_f32 v[4:5], v[4:5], v[226:227]
	v_pk_mul_f32 v[14:15], v[14:15], v[220:221]
	v_pk_mul_f32 v[10:11], v[10:11], v[224:225]
	v_pk_mul_f32 v[6:7], v[6:7], v[228:229]
	s_waitcnt lgkmcnt(0)
	v_pk_mul_f32 v[2:3], v[2:3], v[232:233]
	v_pk_mul_f32 v[0:1], v[0:1], v[230:231]
	v_pk_mul_f32 v[60:61], v[60:61], v[218:219]
	v_pk_mul_f32 v[56:57], v[56:57], v[222:223]
	v_pk_mul_f32 v[52:53], v[52:53], v[226:227]
	v_pk_mul_f32 v[62:63], v[62:63], v[220:221]
	v_pk_mul_f32 v[58:59], v[58:59], v[224:225]
	v_pk_mul_f32 v[54:55], v[54:55], v[228:229]
	v_pk_mul_f32 v[50:51], v[50:51], v[232:233]
	v_pk_mul_f32 v[48:49], v[48:49], v[230:231]
	v_pk_mul_f32 v[44:45], v[44:45], v[218:219]
	v_pk_mul_f32 v[40:41], v[40:41], v[222:223]
	v_pk_mul_f32 v[36:37], v[36:37], v[226:227]
	v_pk_mul_f32 v[46:47], v[46:47], v[220:221]
	v_pk_mul_f32 v[42:43], v[42:43], v[224:225]
	v_pk_mul_f32 v[38:39], v[38:39], v[228:229]
	v_pk_mul_f32 v[34:35], v[34:35], v[232:233]
	v_pk_mul_f32 v[32:33], v[32:33], v[230:231]
	v_pk_mul_f32 v[28:29], v[28:29], v[218:219]
	v_pk_mul_f32 v[24:25], v[24:25], v[222:223]
	v_pk_mul_f32 v[20:21], v[20:21], v[226:227]
	v_pk_mul_f32 v[30:31], v[30:31], v[220:221]
	v_pk_mul_f32 v[26:27], v[26:27], v[224:225]
	v_pk_mul_f32 v[22:23], v[22:23], v[228:229]
	v_pk_mul_f32 v[18:19], v[18:19], v[232:233]
	v_pk_mul_f32 v[16:17], v[16:17], v[230:231]
.LBB0_437:
	s_waitcnt lgkmcnt(0)
	s_barrier
	ds_read_b128 v[64:67], v166 offset:32768
	ds_read_b128 v[68:71], v166 offset:40960
	ds_read_b128 v[196:199], v167 offset:32768
	ds_read_b128 v[200:203], v167 offset:40960
	ds_read_b128 v[204:207], v168 offset:32768
	ds_read_b128 v[210:213], v168 offset:40960
	v_exp_f32_e32 v188, v188
	v_exp_f32_e32 v189, v189
	s_waitcnt lgkmcnt(5)
	v_mfma_f32_32x32x16_bf16 v[80:95], v[64:67], v[124:127], 0
	v_exp_f32_e32 v190, v190
	v_exp_f32_e32 v191, v191
	v_exp_f32_e32 v192, v192
	v_exp_f32_e32 v195, v181
	v_exp_f32_e32 v182, v182
	v_exp_f32_e32 v183, v183
	v_exp_f32_e32 v184, v184
	s_waitcnt lgkmcnt(4)
	v_mfma_f32_32x32x16_bf16 v[64:79], v[68:71], v[124:127], 0
	v_exp_f32_e32 v185, v185
	v_exp_f32_e32 v186, v186
	v_exp_f32_e32 v187, v187
	v_exp_f32_e32 v193, v193
	v_exp_f32_e32 v194, v194
	v_exp_f32_e32 v177, v177
	s_waitcnt lgkmcnt(3)
	v_mfma_f32_32x32x16_bf16 v[80:95], v[196:199], v[120:123], v[80:95]
	ds_read_b128 v[196:199], v169 offset:32768
	ds_read_b128 v[214:217], v169 offset:40960
	ds_read_b128 v[218:221], v170 offset:32768
	ds_read_b128 v[222:225], v170 offset:40960
	ds_read_b128 v[226:229], v171 offset:32768
	ds_read_b128 v[230:233], v171 offset:40960
	ds_read_b128 v[234:237], v172 offset:32768
	ds_read_b128 v[238:241], v172 offset:40960
	s_waitcnt lgkmcnt(10)
	v_mfma_f32_32x32x16_bf16 v[64:79], v[200:203], v[120:123], v[64:79]
	ds_read_b128 v[200:203], v173 offset:32768
	ds_read_b128 v[242:245], v173 offset:40960
	s_waitcnt lgkmcnt(11)
	v_mfma_f32_32x32x16_bf16 v[80:95], v[204:207], v[112:115], v[80:95]
	v_exp_f32_e32 v204, v180
	v_add_f32_e32 v180, v144, v143
	v_add_f32_e32 v180, v145, v180
	v_add_f32_e32 v180, v146, v180
	v_add_f32_e32 v180, v147, v180
	v_add_f32_e32 v180, v149, v180
	s_waitcnt lgkmcnt(10)
	v_mfma_f32_32x32x16_bf16 v[64:79], v[210:213], v[112:115], v[64:79]
	v_add_f32_e32 v180, v148, v180
	v_add_f32_e32 v180, v175, v180
	v_add_f32_e32 v180, v135, v180
	v_add_f32_e32 v180, v136, v180
	v_add_f32_e32 v180, v137, v180
	v_add_f32_e32 v180, v139, v180
	v_add_f32_e32 v180, v138, v180
	s_waitcnt lgkmcnt(9)
	v_mfma_f32_32x32x16_bf16 v[80:95], v[196:199], v[116:119], v[80:95]
	v_add_f32_e32 v180, v140, v180
	v_add_f32_e32 v180, v141, v180
	v_add_f32_e32 v180, v142, v180
	v_add_f32_e32 v180, v188, v180
	v_add_f32_e32 v180, v189, v180
	v_add_f32_e32 v180, v190, v180
	v_add_f32_e32 v180, v191, v180
	s_waitcnt lgkmcnt(8)
	v_mfma_f32_32x32x16_bf16 v[64:79], v[214:217], v[116:119], v[64:79]
	v_add_f32_e32 v180, v192, v180
	v_add_f32_e32 v180, v195, v180
	v_add_f32_e32 v180, v182, v180
	v_add_f32_e32 v180, v183, v180
	v_add_f32_e32 v180, v184, v180
	v_add_f32_e32 v180, v185, v180
	v_add_f32_e32 v180, v186, v180
	s_waitcnt lgkmcnt(7)
	v_mfma_f32_32x32x16_bf16 v[80:95], v[218:221], v[108:111], v[80:95]
	v_add_f32_e32 v180, v187, v180
	v_add_f32_e32 v180, v204, v180
	v_add_f32_e32 v180, v193, v180
	v_add_f32_e32 v180, v194, v180
	v_add_f32_e32 v180, v177, v180
	s_waitcnt lgkmcnt(6)
	v_mfma_f32_32x32x16_bf16 v[64:79], v[222:225], v[108:111], v[64:79]
	v_cvt_pk_bf16_f32 v144, v143, v144
	v_cvt_pk_bf16_f32 v145, v145, v146
	v_cvt_pk_bf16_f32 v146, v147, v149
	v_cvt_pk_bf16_f32 v147, v148, v175
	v_cvt_pk_bf16_f32 v136, v135, v136
	v_cvt_pk_bf16_f32 v137, v137, v139
	v_cvt_pk_bf16_f32 v138, v138, v140
	s_waitcnt lgkmcnt(5)
	v_mfma_f32_32x32x16_bf16 v[80:95], v[226:229], v[104:107], v[80:95]
	v_cvt_pk_bf16_f32 v139, v141, v142
	v_cvt_pk_bf16_f32 v140, v188, v189
	v_cvt_pk_bf16_f32 v141, v190, v191
	v_cvt_pk_bf16_f32 v142, v192, v195
	v_cvt_pk_bf16_f32 v143, v182, v183
	v_cvt_pk_bf16_f32 v182, v184, v185
	v_cvt_pk_bf16_f32 v183, v186, v187
	s_waitcnt lgkmcnt(4)
	v_mfma_f32_32x32x16_bf16 v[64:79], v[230:233], v[104:107], v[64:79]
	v_cvt_pk_bf16_f32 v184, v204, v193
	v_cvt_pk_bf16_f32 v185, v194, v177
	s_waitcnt lgkmcnt(3)
	v_mfma_f32_32x32x16_bf16 v[80:95], v[234:237], v[100:103], v[80:95]
	s_waitcnt lgkmcnt(2)
	v_mfma_f32_32x32x16_bf16 v[64:79], v[238:241], v[100:103], v[64:79]
	s_waitcnt lgkmcnt(1)
	v_mfma_f32_32x32x16_bf16 v[80:95], v[200:203], v[96:99], v[80:95]
	s_waitcnt lgkmcnt(0)
	v_mfma_f32_32x32x16_bf16 v[64:79], v[242:245], v[96:99], v[64:79]
	global_load_dwordx4 v[226:229], v132, s[28:29]
	global_load_dwordx4 v[230:233], v132, s[30:31]
	global_load_dwordx4 v[234:237], v133, s[28:29]
	global_load_dwordx4 v[238:241], v133, s[30:31]
	s_add_u32 s28, s28, 0x8000
	s_addc_u32 s29, s29, 0
	s_add_u32 s30, s30, 0x8000
	s_addc_u32 s31, s31, 0
	ds_read_b64_tr_b16 v[202:203], v160 offset:0
	ds_read_b64_tr_b16 v[204:205], v160 offset:0x800
	ds_read_b64_tr_b16 v[210:211], v160 offset:0x1000
	ds_read_b64_tr_b16 v[212:213], v160 offset:0x1800
	ds_read_b64_tr_b16 v[214:215], v160 offset:0x2000
	ds_read_b64_tr_b16 v[216:217], v160 offset:0x2800
	ds_read_b64_tr_b16 v[218:219], v160 offset:0x3000
	ds_read_b64_tr_b16 v[220:221], v160 offset:0x3800
	s_nop 0
	s_waitcnt lgkmcnt(6)
	v_mfma_f32_32x32x16_bf16 v[0:15], v[144:147], v[202:205], v[0:15]
	ds_read_b64_tr_b16 v[202:203], v160 offset:0x200
	ds_read_b64_tr_b16 v[204:205], v160 offset:0xa00
	v_max_f32_e32 v242, v80, v81
	v_max3_f32 v242, v242, v82, v83
	v_max3_f32 v242, v242, v84, v85
	v_max3_f32 v242, v242, v86, v87
	v_max3_f32 v242, v242, v88, v89
	s_waitcnt lgkmcnt(6)
	v_mfma_f32_32x32x16_bf16 v[0:15], v[136:139], v[210:213], v[0:15]
	ds_read_b64_tr_b16 v[210:211], v160 offset:0x1200
	ds_read_b64_tr_b16 v[212:213], v160 offset:0x1a00
	v_max3_f32 v242, v242, v90, v91
	v_max3_f32 v242, v242, v92, v93
	v_max3_f32 v242, v242, v94, v95
	v_max3_f32 v242, v242, v64, v65
	v_max3_f32 v242, v242, v66, v67
	s_waitcnt lgkmcnt(6)
	v_mfma_f32_32x32x16_bf16 v[0:15], v[140:143], v[214:217], v[0:15]
	ds_read_b64_tr_b16 v[214:215], v160 offset:0x2200
	ds_read_b64_tr_b16 v[216:217], v160 offset:0x2a00
	ds_read_b64_tr_b16 v[222:223], v160 offset:0x3200
	ds_read_b64_tr_b16 v[224:225], v160 offset:0x3a00
	v_max3_f32 v242, v242, v68, v69
	v_max3_f32 v242, v242, v70, v71
	v_max3_f32 v242, v242, v72, v73
	v_max3_f32 v242, v242, v74, v75
	v_max3_f32 v242, v242, v76, v77
	s_waitcnt lgkmcnt(8)
	v_mfma_f32_32x32x16_bf16 v[0:15], v[182:185], v[218:221], v[0:15]
	v_max3_f32 v242, v242, v78, v79
	v_mov_b32_e32 v243, v242
	s_waitcnt lgkmcnt(6)
	v_mfma_f32_32x32x16_bf16 v[48:63], v[144:147], v[202:205], v[48:63]
	ds_read_b64_tr_b16 v[202:203], v160 offset:0x400
	ds_read_b64_tr_b16 v[204:205], v160 offset:0xc00
	v_permlane32_swap_b32_e32 v242, v243
	v_max_f32_e32 v242, v242, v243
	s_waitcnt lgkmcnt(6)
	v_mfma_f32_32x32x16_bf16 v[48:63], v[136:139], v[210:213], v[48:63]
	ds_read_b64_tr_b16 v[210:211], v160 offset:0x1400
	ds_read_b64_tr_b16 v[212:213], v160 offset:0x1c00
	v_sub_f32_e32 v243, v242, v134
	v_max_f32_e32 v242, v134, v242
	v_sub_f32_e32 v148, v134, v242
	v_mul_f32_e32 v148, 0x3e0293ee, v148
	s_waitcnt lgkmcnt(6)
	v_mfma_f32_32x32x16_bf16 v[48:63], v[140:143], v[214:217], v[48:63]
	ds_read_b64_tr_b16 v[214:215], v160 offset:0x2400
	ds_read_b64_tr_b16 v[216:217], v160 offset:0x2c00
	ds_read_b64_tr_b16 v[218:219], v160 offset:0x3400
	ds_read_b64_tr_b16 v[220:221], v160 offset:0x3c00
	v_exp_f32_e32 v148, v148
	v_cmp_ge_f32_e32 vcc, s15, v243
	s_cmp_eq_u64 vcc, exec
	s_cselect_b64 s[8:9], -1, 0
	s_waitcnt lgkmcnt(8)
	v_mfma_f32_32x32x16_bf16 v[48:63], v[182:185], v[222:225], v[48:63]
	v_cndmask_b32_e64 v177, v148, 1.0, s[8:9]
	v_cndmask_b32_e64 v175, v242, v134, s[8:9]
	v_mul_f32_e32 v244, 0xbe0293ee, v175
	v_fmamk_f32 v80, v80, 0x3e0293ee, v244
	v_fmamk_f32 v81, v81, 0x3e0293ee, v244
	v_fmamk_f32 v82, v82, 0x3e0293ee, v244
	v_fmamk_f32 v83, v83, 0x3e0293ee, v244
	s_waitcnt lgkmcnt(6)
	v_mfma_f32_32x32x16_bf16 v[32:47], v[144:147], v[202:205], v[32:47]
	ds_read_b64_tr_b16 v[202:203], v160 offset:0x600
	ds_read_b64_tr_b16 v[204:205], v160 offset:0xe00
	v_fmamk_f32 v84, v84, 0x3e0293ee, v244
	v_fmamk_f32 v85, v85, 0x3e0293ee, v244
	v_fmamk_f32 v86, v86, 0x3e0293ee, v244
	v_fmamk_f32 v87, v87, 0x3e0293ee, v244
	v_fmamk_f32 v88, v88, 0x3e0293ee, v244
	v_fmamk_f32 v89, v89, 0x3e0293ee, v244
	v_fmamk_f32 v90, v90, 0x3e0293ee, v244
	v_fmamk_f32 v91, v91, 0x3e0293ee, v244
	s_waitcnt lgkmcnt(6)
	v_mfma_f32_32x32x16_bf16 v[32:47], v[136:139], v[210:213], v[32:47]
	ds_read_b64_tr_b16 v[210:211], v160 offset:0x1600
	ds_read_b64_tr_b16 v[212:213], v160 offset:0x1e00
	v_fmamk_f32 v92, v92, 0x3e0293ee, v244
	v_fmamk_f32 v93, v93, 0x3e0293ee, v244
	v_fmamk_f32 v94, v94, 0x3e0293ee, v244
	v_fmamk_f32 v95, v95, 0x3e0293ee, v244
	v_fmamk_f32 v134, v72, 0x3e0293ee, v244
	v_fmamk_f32 v135, v73, 0x3e0293ee, v244
	v_fmamk_f32 v148, v74, 0x3e0293ee, v244
	v_fmamk_f32 v149, v75, 0x3e0293ee, v244
	s_waitcnt lgkmcnt(6)
	v_mfma_f32_32x32x16_bf16 v[32:47], v[140:143], v[214:217], v[32:47]
	ds_read_b64_tr_b16 v[214:215], v160 offset:0x2600
	ds_read_b64_tr_b16 v[216:217], v160 offset:0x2e00
	ds_read_b64_tr_b16 v[222:223], v160 offset:0x3600
	ds_read_b64_tr_b16 v[224:225], v160 offset:0x3e00
	v_exp_f32_e32 v190, v80
	v_exp_f32_e32 v191, v81
	v_exp_f32_e32 v192, v82
	s_waitcnt lgkmcnt(8)
	v_mfma_f32_32x32x16_bf16 v[32:47], v[182:185], v[218:221], v[32:47]
	v_exp_f32_e32 v193, v83
	v_exp_f32_e32 v194, v84
	v_exp_f32_e32 v196, v85
	s_waitcnt lgkmcnt(6)
	v_mfma_f32_32x32x16_bf16 v[16:31], v[144:147], v[202:205], v[16:31]
	v_fmamk_f32 v144, v78, 0x3e0293ee, v244
	v_fmamk_f32 v145, v79, 0x3e0293ee, v244
	v_fmamk_f32 v146, v76, 0x3e0293ee, v244
	v_fmamk_f32 v147, v77, 0x3e0293ee, v244
	v_exp_f32_e32 v195, v86
	v_exp_f32_e32 v197, v87
	s_waitcnt lgkmcnt(4)
	v_mfma_f32_32x32x16_bf16 v[16:31], v[136:139], v[210:213], v[16:31]
	v_fmamk_f32 v136, v70, 0x3e0293ee, v244
	v_fmamk_f32 v137, v71, 0x3e0293ee, v244
	v_fmamk_f32 v138, v68, 0x3e0293ee, v244
	v_fmamk_f32 v139, v69, 0x3e0293ee, v244
	v_exp_f32_e32 v186, v91
	v_exp_f32_e32 v187, v93
	s_waitcnt lgkmcnt(2)
	v_mfma_f32_32x32x16_bf16 v[16:31], v[140:143], v[214:217], v[16:31]
	v_fmamk_f32 v140, v66, 0x3e0293ee, v244
	v_fmamk_f32 v141, v67, 0x3e0293ee, v244
	v_fmamk_f32 v142, v64, 0x3e0293ee, v244
	v_fmamk_f32 v143, v65, 0x3e0293ee, v244
	v_exp_f32_e32 v188, v94
	v_exp_f32_e32 v189, v95
	s_waitcnt lgkmcnt(0)
	v_mfma_f32_32x32x16_bf16 v[16:31], v[182:185], v[222:225], v[16:31]
	v_exp_f32_e32 v182, v88
	v_exp_f32_e32 v183, v89
	v_exp_f32_e32 v184, v90
	v_exp_f32_e32 v185, v92
	v_cmp_gt_f32_e32 vcc, 1.0, v177
	s_waitcnt vmcnt(0)
	ds_write_b128 v162, v[230:233] offset:49152
	ds_write_b128 v163, v[238:241] offset:49152
	s_barrier
	s_waitcnt vmcnt(0)
	ds_write_b128 v164, v[226:229] offset:16384
	ds_write_b128 v165, v[234:237] offset:16384
	s_cbranch_vccz .LBB0_441
	s_and_saveexec_b64 s[2:3], s[6:7]
	ds_write_b32 v158, v177 offset:128
	s_or_b64 exec, exec, s[2:3]
	s_waitcnt lgkmcnt(0)
	v_add_u32_e32 v242, v131, v128
	ds_read_b128 v[226:229], v242 offset:224
	ds_read_b128 v[230:233], v242 offset:192
	ds_read_b128 v[234:237], v242 offset:160
	ds_read_b128 v[238:241], v242 offset:128
	s_waitcnt lgkmcnt(3)
	v_pk_mul_f32 v[12:13], v[12:13], v[226:227]
	s_waitcnt lgkmcnt(2)
	v_pk_mul_f32 v[8:9], v[8:9], v[230:231]
	s_waitcnt lgkmcnt(1)
	v_pk_mul_f32 v[4:5], v[4:5], v[234:235]
	v_pk_mul_f32 v[14:15], v[14:15], v[228:229]
	v_pk_mul_f32 v[10:11], v[10:11], v[232:233]
	v_pk_mul_f32 v[6:7], v[6:7], v[236:237]
	s_waitcnt lgkmcnt(0)
	v_pk_mul_f32 v[2:3], v[2:3], v[240:241]
	v_pk_mul_f32 v[0:1], v[0:1], v[238:239]
	v_pk_mul_f32 v[60:61], v[60:61], v[226:227]
	v_pk_mul_f32 v[56:57], v[56:57], v[230:231]
	v_pk_mul_f32 v[52:53], v[52:53], v[234:235]
	v_pk_mul_f32 v[62:63], v[62:63], v[228:229]
	v_pk_mul_f32 v[58:59], v[58:59], v[232:233]
	v_pk_mul_f32 v[54:55], v[54:55], v[236:237]
	v_pk_mul_f32 v[50:51], v[50:51], v[240:241]
	v_pk_mul_f32 v[48:49], v[48:49], v[238:239]
	v_pk_mul_f32 v[44:45], v[44:45], v[226:227]
	v_pk_mul_f32 v[40:41], v[40:41], v[230:231]
	v_pk_mul_f32 v[36:37], v[36:37], v[234:235]
	v_pk_mul_f32 v[46:47], v[46:47], v[228:229]
	v_pk_mul_f32 v[42:43], v[42:43], v[232:233]
	v_pk_mul_f32 v[38:39], v[38:39], v[236:237]
	v_pk_mul_f32 v[34:35], v[34:35], v[240:241]
	v_pk_mul_f32 v[32:33], v[32:33], v[238:239]
	v_pk_mul_f32 v[28:29], v[28:29], v[226:227]
	v_pk_mul_f32 v[24:25], v[24:25], v[230:231]
	v_pk_mul_f32 v[20:21], v[20:21], v[234:235]
	v_pk_mul_f32 v[30:31], v[30:31], v[228:229]
	v_pk_mul_f32 v[26:27], v[26:27], v[232:233]
	v_pk_mul_f32 v[22:23], v[22:23], v[236:237]
	v_pk_mul_f32 v[18:19], v[18:19], v[240:241]
	v_pk_mul_f32 v[16:17], v[16:17], v[238:239]
